# gate|up phases: the first K-loop trip after a SwiGLU epilogue runs a copy of the loop body whose first two counted waits (vmcnt 8 -> 17) no longer wait for the epilogue's stores
# baseline (speedup 1.0000x reference)
.LBB0_347:
	v_lshrrev_b32_e32 v4, 1, v2
	v_and_b32_e32 v151, 24, v4
	s_add_u32 s20, s16, 0x5000000
	v_and_b32_e32 v3, 63, v2
	v_and_b32_e32 v149, 15, v2
	v_lshlrev_b32_e32 v4, 1, v151
	v_lshlrev_b32_e32 v2, 2, v2
	s_addc_u32 s21, s17, 0
	s_lshl_b32 s39, s0, 6
	v_lshl_or_b32 v4, v149, 6, v4
	s_lshl_b32 s0, s0, 13
	v_and_b32_e32 v2, 32, v2
	v_bitop3_b32 v5, v4, s0, v2 bitop3:0xde
	s_lshl_b32 s0, s25, 5
	s_and_b32 s40, s0, 0x60
	s_lshl_b32 s0, s40, 7
	v_bitop3_b32 v4, v4, s0, v2 bitop3:0xde
	s_waitcnt vmcnt(2)
	s_barrier
	s_add_i32 s41, s33, 0x18000
	s_or_b32 s0, s64, 0x80
	s_mov_b32 m0, s41
	s_nop 0
	buffer_load_dwordx4 v145, s[8:11], s0 offen lds
	s_add_i32 s42, s33, 0x1a000
	s_mov_b32 m0, s42
	s_nop 0
	buffer_load_dwordx4 v146, s[8:11], s0 offen lds
	s_add_i32 s43, s33, 0x8000
	s_or_b32 s0, s63, 0x80
	s_mov_b32 m0, s43
	s_nop 0
	buffer_load_dwordx4 v147, s[12:15], s0 offen lds
	s_add_i32 s44, s33, 0xa000
	s_mov_b32 m0, s44
	s_nop 0
	buffer_load_dwordx4 v148, s[12:15], s0 offen lds
	s_add_i32 s45, s33, 0x1c000
	s_or_b32 s0, s64, 0x20080
	s_add_i32 s46, s33, 0x1e000
	s_cmp_lt_i32 s25, 4
	s_cselect_b64 s[22:23], -1, 0
	s_and_b32 s4, s24, 0xffffffc0
	s_lshl_b32 s47, s25, 8
	s_add_i32 s48, s33, 0xc000
	s_add_i32 s5, s4, 0xffffff00
	s_ashr_i32 s26, s4, 31
	s_cmpk_lt_u32 s24, 0x100
	s_mov_b32 m0, s45
	s_nop 0
	buffer_load_dwordx4 v145, s[8:11], s0 offen lds
	s_cselect_b64 s[24:25], -1, 0
	s_add_i32 s49, s33, 0xe000
	s_ashr_i32 s50, s30, 31
	s_mov_b32 m0, s46
	s_nop 0
	buffer_load_dwordx4 v146, s[8:11], s0 offen lds
	s_mov_b32 s51, 0xfc00000
	s_and_b64 s[0:1], s[22:23], exec
	s_cselect_b32 s0, s51, 0xfc20000
	s_add_u32 s51, s16, s0
	s_addc_u32 s52, s17, 0
	s_and_b64 s[0:1], s[22:23], exec
	s_cselect_b32 s1, s26, 0
	s_cselect_b32 s0, s4, s5
	s_lshl_b64 s[0:1], s[0:1], 2
	s_add_u32 s0, s51, s0
	s_waitcnt vmcnt(6)
	s_addc_u32 s1, s52, s1
	v_lshlrev_b32_e32 v2, 2, v3
	v_mov_b32_e32 v3, 0
	v_lshl_add_u64 v[130:131], s[0:1], 0, v[2:3]
	v_add_u32_e32 v2, 0, v4
	v_or_b32_e32 v150, s39, v149
	v_or_b32_e32 v152, s40, v151
	v_mov_b64_e32 v[132:133], 0x580
	v_mov_b64_e32 v[134:135], 0x57f
	s_movk_i32 s51, 0xb1
	v_add_u32_e32 v153, 0x10000, v2
	v_add_u32_e32 v154, 0x14000, v2
	v_add_u32_e32 v155, 0, v5
	v_add_u32_e32 v156, 0x18000, v2
	v_add_u32_e32 v157, 0x1c000, v2
	s_movk_i32 s52, 0x1600
	s_mov_b32 s26, 0xbfb8aa3b
	s_barrier
	s_mov_b32 s32, 0
	s_branch .LBB0_350

.LBB0_349:
	s_mov_b32 s32, 1
	s_andn2_b64 vcc, exec, s[0:1]
	s_mov_b32 s60, s54
	s_mov_b32 s61, s55
	s_mov_b32 s64, s59
	s_mov_b32 s63, s58
	s_mov_b32 s58, s53
	s_cbranch_vccz .LBB0_359

.LBB0_352:
	s_and_b64 s[0:1], s[22:23], exec
	s_cselect_b32 s0, s61, s60
	s_lshl_b32 s0, s0, 8
	s_ashr_i32 s1, s0, 31
	v_lshl_add_u64 v[2:3], s[0:1], 2, v[130:131]
	s_lshl_b32 s0, s58, 11
	s_and_b32 s0, s0, 0x800
	s_add_i32 s0, s0, 0
	s_add_i32 s0, s0, 0x20000
	s_add_i32 m0, s0, s47
	s_lshl_b32 s58, s55, 19
	global_load_lds_dword v[2:3], off
	s_or_b32 s1, s63, 0x300
	s_and_b64 s[66:67], s[4:5], exec
	s_cselect_b32 s1, s58, s1
	s_lshl_b32 s59, s54, 18
	s_or_b32 s62, s64, 0x300
	s_and_b64 s[66:67], s[4:5], exec
	v_mov_b32_e32 v2, 0
	s_cselect_b32 s62, s59, s62
	s_add_i32 s63, s63, 0x20080
	s_addk_i32 s64, 0x100
	s_mov_b32 s65, -2
	v_mov_b32_e32 v3, v2
	v_mov_b32_e32 v4, v2
	v_mov_b32_e32 v5, v2
	v_mov_b32_e32 v6, v2
	v_mov_b32_e32 v7, v2
	v_mov_b32_e32 v8, v2
	v_mov_b32_e32 v9, v2
	v_mov_b32_e32 v10, v2
	v_mov_b32_e32 v11, v2
	v_mov_b32_e32 v12, v2
	v_mov_b32_e32 v13, v2
	v_mov_b32_e32 v14, v2
	v_mov_b32_e32 v15, v2
	v_mov_b32_e32 v16, v2
	v_mov_b32_e32 v17, v2
	v_mov_b32_e32 v18, v2
	v_mov_b32_e32 v19, v2
	v_mov_b32_e32 v20, v2
	v_mov_b32_e32 v21, v2
	v_mov_b32_e32 v22, v2
	v_mov_b32_e32 v23, v2
	v_mov_b32_e32 v24, v2
	v_mov_b32_e32 v25, v2
	v_mov_b32_e32 v26, v2
	v_mov_b32_e32 v27, v2
	v_mov_b32_e32 v28, v2
	v_mov_b32_e32 v29, v2
	v_mov_b32_e32 v30, v2
	v_mov_b32_e32 v31, v2
	v_mov_b32_e32 v32, v2
	v_mov_b32_e32 v33, v2
	v_mov_b32_e32 v34, v2
	v_mov_b32_e32 v35, v2
	v_mov_b32_e32 v36, v2
	v_mov_b32_e32 v37, v2
	v_mov_b32_e32 v38, v2
	v_mov_b32_e32 v39, v2
	v_mov_b32_e32 v40, v2
	v_mov_b32_e32 v41, v2
	v_mov_b32_e32 v42, v2
	v_mov_b32_e32 v43, v2
	v_mov_b32_e32 v44, v2
	v_mov_b32_e32 v45, v2
	v_mov_b32_e32 v46, v2
	v_mov_b32_e32 v47, v2
	v_mov_b32_e32 v48, v2
	v_mov_b32_e32 v49, v2
	v_mov_b32_e32 v50, v2
	v_mov_b32_e32 v51, v2
	v_mov_b32_e32 v52, v2
	v_mov_b32_e32 v53, v2
	v_mov_b32_e32 v54, v2
	v_mov_b32_e32 v55, v2
	v_mov_b32_e32 v56, v2
	v_mov_b32_e32 v57, v2
	v_mov_b32_e32 v58, v2
	v_mov_b32_e32 v59, v2
	v_mov_b32_e32 v60, v2
	v_mov_b32_e32 v61, v2
	v_mov_b32_e32 v62, v2
	v_mov_b32_e32 v63, v2
	v_mov_b32_e32 v64, v2
	v_mov_b32_e32 v65, v2
	v_mov_b32_e32 v66, v2
	v_mov_b32_e32 v67, v2
	v_mov_b32_e32 v68, v2
	v_mov_b32_e32 v69, v2
	v_mov_b32_e32 v70, v2
	v_mov_b32_e32 v71, v2
	v_mov_b32_e32 v72, v2
	v_mov_b32_e32 v73, v2
	v_mov_b32_e32 v74, v2
	v_mov_b32_e32 v75, v2
	v_mov_b32_e32 v76, v2
	v_mov_b32_e32 v77, v2
	v_mov_b32_e32 v78, v2
	v_mov_b32_e32 v79, v2
	v_mov_b32_e32 v80, v2
	v_mov_b32_e32 v81, v2
	v_mov_b32_e32 v82, v2
	v_mov_b32_e32 v83, v2
	v_mov_b32_e32 v84, v2
	v_mov_b32_e32 v85, v2
	v_mov_b32_e32 v86, v2
	v_mov_b32_e32 v87, v2
	v_mov_b32_e32 v88, v2
	v_mov_b32_e32 v89, v2
	v_mov_b32_e32 v90, v2
	v_mov_b32_e32 v91, v2
	v_mov_b32_e32 v92, v2
	v_mov_b32_e32 v93, v2
	v_mov_b32_e32 v94, v2
	v_mov_b32_e32 v95, v2
	v_mov_b32_e32 v96, v2
	v_mov_b32_e32 v97, v2
	v_mov_b32_e32 v98, v2
	v_mov_b32_e32 v99, v2
	v_mov_b32_e32 v100, v2
	v_mov_b32_e32 v101, v2
	v_mov_b32_e32 v102, v2
	v_mov_b32_e32 v103, v2
	v_mov_b32_e32 v104, v2
	v_mov_b32_e32 v105, v2
	v_mov_b32_e32 v106, v2
	v_mov_b32_e32 v107, v2
	v_mov_b32_e32 v108, v2
	v_mov_b32_e32 v109, v2
	v_mov_b32_e32 v110, v2
	v_mov_b32_e32 v111, v2
	v_mov_b32_e32 v112, v2
	v_mov_b32_e32 v113, v2
	v_mov_b32_e32 v114, v2
	v_mov_b32_e32 v115, v2
	v_mov_b32_e32 v116, v2
	v_mov_b32_e32 v117, v2
	v_mov_b32_e32 v118, v2
	v_mov_b32_e32 v119, v2
	v_mov_b32_e32 v120, v2
	v_mov_b32_e32 v121, v2
	v_mov_b32_e32 v122, v2
	v_mov_b32_e32 v123, v2
	v_mov_b32_e32 v124, v2
	v_mov_b32_e32 v125, v2
	v_mov_b32_e32 v126, v2
	v_mov_b32_e32 v127, v2
	v_mov_b32_e32 v128, v2
	v_mov_b32_e32 v129, v2
	s_cmp_eq_u32 s32, 1
	s_cbranch_scc1 .Lpeel5

.Lafter5:
	s_and_b64 vcc, exec, s[24:25]
	s_cbranch_vccz .LBB0_356
	s_barrier

.Lpeel5:
	ds_read_b128 v[136:139], v153
	ds_read_b128 v[140:143], v153 offset:1024
	ds_read_b128 v[158:161], v153 offset:2048
	ds_read_b128 v[162:165], v153 offset:3072
	ds_read_b128 v[166:169], v154
	ds_read_b128 v[170:173], v154 offset:1024
	ds_read_b128 v[174:177], v154 offset:2048
	ds_read_b128 v[178:181], v154 offset:3072
	s_add_i32 s66, s63, 0xfffe0080
	s_cmp_eq_u32 s65, 4
	s_cselect_b32 s68, s1, s66
	s_cselect_b32 s67, s62, s64
	s_or_b32 s66, s68, 0x80
	ds_read_b128 v[182:185], v155
	ds_read_b128 v[186:189], v155 offset:1024
	ds_read_b128 v[190:193], v155 offset:2048
	ds_read_b128 v[194:197], v155 offset:3072
	ds_read_b128 v[198:201], v155 offset:4096
	ds_read_b128 v[202:205], v155 offset:5120
	ds_read_b128 v[206:209], v155 offset:6144
	ds_read_b128 v[210:213], v155 offset:7168
	s_mov_b32 m0, s48
	s_nop 0
	buffer_load_dwordx4 v147, s[12:15], s63 offen lds
	s_nop 0
	s_mov_b32 m0, s49
	s_nop 0
	buffer_load_dwordx4 v148, s[12:15], s63 offen lds
	s_waitcnt vmcnt(17)
	s_waitcnt lgkmcnt(0)
	s_barrier
	s_setprio 1
	s_waitcnt lgkmcnt(0)
	v_mfma_i32_16x16x64_i8 v[126:129], v[136:139], v[182:185], v[126:129]
	v_mfma_i32_16x16x64_i8 v[122:125], v[158:161], v[182:185], v[122:125]
	v_mfma_i32_16x16x64_i8 v[118:121], v[136:139], v[190:193], v[118:121]
	v_mfma_i32_16x16x64_i8 v[114:117], v[158:161], v[190:193], v[114:117]
	v_mfma_i32_16x16x64_i8 v[110:113], v[136:139], v[198:201], v[110:113]
	v_mfma_i32_16x16x64_i8 v[106:109], v[158:161], v[198:201], v[106:109]
	v_mfma_i32_16x16x64_i8 v[102:105], v[136:139], v[206:209], v[102:105]
	v_mfma_i32_16x16x64_i8 v[98:101], v[158:161], v[206:209], v[98:101]
	v_mfma_i32_16x16x64_i8 v[126:129], v[140:143], v[186:189], v[126:129]
	v_mfma_i32_16x16x64_i8 v[122:125], v[162:165], v[186:189], v[122:125]
	v_mfma_i32_16x16x64_i8 v[118:121], v[140:143], v[194:197], v[118:121]
	v_mfma_i32_16x16x64_i8 v[114:117], v[162:165], v[194:197], v[114:117]
	v_mfma_i32_16x16x64_i8 v[110:113], v[140:143], v[202:205], v[110:113]
	v_mfma_i32_16x16x64_i8 v[106:109], v[162:165], v[202:205], v[106:109]
	v_mfma_i32_16x16x64_i8 v[102:105], v[140:143], v[210:213], v[102:105]
	v_mfma_i32_16x16x64_i8 v[98:101], v[162:165], v[210:213], v[98:101]
	s_setprio 0
	s_setprio 1
	v_mfma_i32_16x16x64_i8 v[94:97], v[166:169], v[182:185], v[94:97]
	v_mfma_i32_16x16x64_i8 v[90:93], v[174:177], v[182:185], v[90:93]
	v_mfma_i32_16x16x64_i8 v[86:89], v[166:169], v[190:193], v[86:89]
	v_mfma_i32_16x16x64_i8 v[82:85], v[174:177], v[190:193], v[82:85]
	v_mfma_i32_16x16x64_i8 v[78:81], v[166:169], v[198:201], v[78:81]
	v_mfma_i32_16x16x64_i8 v[74:77], v[174:177], v[198:201], v[74:77]
	v_mfma_i32_16x16x64_i8 v[70:73], v[166:169], v[206:209], v[70:73]
	v_mfma_i32_16x16x64_i8 v[66:69], v[174:177], v[206:209], v[66:69]
	v_mfma_i32_16x16x64_i8 v[94:97], v[170:173], v[186:189], v[94:97]
	v_mfma_i32_16x16x64_i8 v[90:93], v[178:181], v[186:189], v[90:93]
	v_mfma_i32_16x16x64_i8 v[86:89], v[170:173], v[194:197], v[86:89]
	v_mfma_i32_16x16x64_i8 v[82:85], v[178:181], v[194:197], v[82:85]
	v_mfma_i32_16x16x64_i8 v[78:81], v[170:173], v[202:205], v[78:81]
	v_mfma_i32_16x16x64_i8 v[74:77], v[178:181], v[202:205], v[74:77]
	v_mfma_i32_16x16x64_i8 v[70:73], v[170:173], v[210:213], v[70:73]
	v_mfma_i32_16x16x64_i8 v[66:69], v[178:181], v[210:213], v[66:69]
	s_setprio 0
	s_barrier
	ds_read_b128 v[182:185], v155 offset:16384
	ds_read_b128 v[186:189], v155 offset:17408
	ds_read_b128 v[190:193], v155 offset:18432
	ds_read_b128 v[194:197], v155 offset:19456
	ds_read_b128 v[198:201], v155 offset:20480
	ds_read_b128 v[202:205], v155 offset:21504
	ds_read_b128 v[206:209], v155 offset:22528
	ds_read_b128 v[210:213], v155 offset:23552
	s_mov_b32 m0, s34
	s_nop 0
	buffer_load_dwordx4 v145, s[8:11], s67 offen lds
	s_add_i32 s69, s67, 0x20000
	s_mov_b32 m0, s35
	s_nop 0
	buffer_load_dwordx4 v146, s[8:11], s67 offen lds
	s_nop 0
	s_mov_b32 m0, s36
	s_nop 0
	buffer_load_dwordx4 v145, s[8:11], s69 offen lds
	s_nop 0
	s_mov_b32 m0, s37
	s_nop 0
	buffer_load_dwordx4 v146, s[8:11], s69 offen lds
	s_nop 0
	s_mov_b32 m0, s33
	s_nop 0
	buffer_load_dwordx4 v147, s[12:15], s68 offen lds
	s_nop 0
	s_mov_b32 m0, s2
	s_nop 0
	buffer_load_dwordx4 v148, s[12:15], s68 offen lds
	s_waitcnt vmcnt(17)
	s_waitcnt lgkmcnt(0)
	s_barrier
	s_setprio 1
	s_waitcnt lgkmcnt(0)
	v_mfma_i32_16x16x64_i8 v[62:65], v[136:139], v[182:185], v[62:65]
	v_mfma_i32_16x16x64_i8 v[58:61], v[158:161], v[182:185], v[58:61]
	v_mfma_i32_16x16x64_i8 v[54:57], v[136:139], v[190:193], v[54:57]
	v_mfma_i32_16x16x64_i8 v[50:53], v[158:161], v[190:193], v[50:53]
	v_mfma_i32_16x16x64_i8 v[46:49], v[136:139], v[198:201], v[46:49]
	v_mfma_i32_16x16x64_i8 v[42:45], v[158:161], v[198:201], v[42:45]
	v_mfma_i32_16x16x64_i8 v[38:41], v[136:139], v[206:209], v[38:41]
	v_mfma_i32_16x16x64_i8 v[34:37], v[158:161], v[206:209], v[34:37]
	v_mfma_i32_16x16x64_i8 v[62:65], v[140:143], v[186:189], v[62:65]
	v_mfma_i32_16x16x64_i8 v[58:61], v[162:165], v[186:189], v[58:61]
	v_mfma_i32_16x16x64_i8 v[54:57], v[140:143], v[194:197], v[54:57]
	v_mfma_i32_16x16x64_i8 v[50:53], v[162:165], v[194:197], v[50:53]
	v_mfma_i32_16x16x64_i8 v[46:49], v[140:143], v[202:205], v[46:49]
	v_mfma_i32_16x16x64_i8 v[42:45], v[162:165], v[202:205], v[42:45]
	v_mfma_i32_16x16x64_i8 v[38:41], v[140:143], v[210:213], v[38:41]
	v_mfma_i32_16x16x64_i8 v[34:37], v[162:165], v[210:213], v[34:37]
	s_setprio 0
	s_setprio 1
	v_mfma_i32_16x16x64_i8 v[30:33], v[166:169], v[182:185], v[30:33]
	v_mfma_i32_16x16x64_i8 v[26:29], v[174:177], v[182:185], v[26:29]
	v_mfma_i32_16x16x64_i8 v[22:25], v[166:169], v[190:193], v[22:25]
	v_mfma_i32_16x16x64_i8 v[18:21], v[174:177], v[190:193], v[18:21]
	v_mfma_i32_16x16x64_i8 v[14:17], v[166:169], v[198:201], v[14:17]
	v_mfma_i32_16x16x64_i8 v[10:13], v[174:177], v[198:201], v[10:13]
	v_mfma_i32_16x16x64_i8 v[6:9], v[166:169], v[206:209], v[6:9]
	v_mfma_i32_16x16x64_i8 v[2:5], v[174:177], v[206:209], v[2:5]
	v_mfma_i32_16x16x64_i8 v[30:33], v[170:173], v[186:189], v[30:33]
	v_mfma_i32_16x16x64_i8 v[26:29], v[178:181], v[186:189], v[26:29]
	v_mfma_i32_16x16x64_i8 v[22:25], v[170:173], v[194:197], v[22:25]
	v_mfma_i32_16x16x64_i8 v[18:21], v[178:181], v[194:197], v[18:21]
	v_mfma_i32_16x16x64_i8 v[14:17], v[170:173], v[202:205], v[14:17]
	v_mfma_i32_16x16x64_i8 v[10:13], v[178:181], v[202:205], v[10:13]
	v_mfma_i32_16x16x64_i8 v[6:9], v[170:173], v[210:213], v[6:9]
	v_mfma_i32_16x16x64_i8 v[2:5], v[178:181], v[210:213], v[2:5]
	s_setprio 0
	s_barrier
	ds_read_b128 v[136:139], v156
	ds_read_b128 v[140:143], v156 offset:1024
	ds_read_b128 v[158:161], v156 offset:2048
	ds_read_b128 v[162:165], v156 offset:3072
	ds_read_b128 v[166:169], v157
	ds_read_b128 v[170:173], v157 offset:1024
	ds_read_b128 v[174:177], v157 offset:2048
	ds_read_b128 v[178:181], v157 offset:3072
	ds_read_b128 v[182:185], v155 offset:32768
	ds_read_b128 v[186:189], v155 offset:33792
	ds_read_b128 v[190:193], v155 offset:34816
	ds_read_b128 v[194:197], v155 offset:35840
	ds_read_b128 v[198:201], v155 offset:36864
	ds_read_b128 v[202:205], v155 offset:37888
	ds_read_b128 v[206:209], v155 offset:38912
	ds_read_b128 v[210:213], v155 offset:39936
	s_add_i32 s68, s68, 0x20000
	s_mov_b32 m0, s3
	s_nop 0
	buffer_load_dwordx4 v147, s[12:15], s68 offen lds
	s_nop 0
	s_mov_b32 m0, s38
	s_nop 0
	buffer_load_dwordx4 v148, s[12:15], s68 offen lds
	s_waitcnt vmcnt(8)
	s_waitcnt lgkmcnt(0)
	s_barrier
	s_setprio 1
	s_waitcnt lgkmcnt(0)
	v_mfma_i32_16x16x64_i8 v[126:129], v[136:139], v[182:185], v[126:129]
	v_mfma_i32_16x16x64_i8 v[122:125], v[158:161], v[182:185], v[122:125]
	v_mfma_i32_16x16x64_i8 v[118:121], v[136:139], v[190:193], v[118:121]
	v_mfma_i32_16x16x64_i8 v[114:117], v[158:161], v[190:193], v[114:117]
	v_mfma_i32_16x16x64_i8 v[110:113], v[136:139], v[198:201], v[110:113]
	v_mfma_i32_16x16x64_i8 v[106:109], v[158:161], v[198:201], v[106:109]
	v_mfma_i32_16x16x64_i8 v[102:105], v[136:139], v[206:209], v[102:105]
	v_mfma_i32_16x16x64_i8 v[98:101], v[158:161], v[206:209], v[98:101]
	v_mfma_i32_16x16x64_i8 v[126:129], v[140:143], v[186:189], v[126:129]
	v_mfma_i32_16x16x64_i8 v[122:125], v[162:165], v[186:189], v[122:125]
	v_mfma_i32_16x16x64_i8 v[118:121], v[140:143], v[194:197], v[118:121]
	v_mfma_i32_16x16x64_i8 v[114:117], v[162:165], v[194:197], v[114:117]
	v_mfma_i32_16x16x64_i8 v[110:113], v[140:143], v[202:205], v[110:113]
	v_mfma_i32_16x16x64_i8 v[106:109], v[162:165], v[202:205], v[106:109]
	v_mfma_i32_16x16x64_i8 v[102:105], v[140:143], v[210:213], v[102:105]
	v_mfma_i32_16x16x64_i8 v[98:101], v[162:165], v[210:213], v[98:101]
	s_setprio 0
	s_setprio 1
	v_mfma_i32_16x16x64_i8 v[94:97], v[166:169], v[182:185], v[94:97]
	v_mfma_i32_16x16x64_i8 v[90:93], v[174:177], v[182:185], v[90:93]
	v_mfma_i32_16x16x64_i8 v[86:89], v[166:169], v[190:193], v[86:89]
	v_mfma_i32_16x16x64_i8 v[82:85], v[174:177], v[190:193], v[82:85]
	v_mfma_i32_16x16x64_i8 v[78:81], v[166:169], v[198:201], v[78:81]
	v_mfma_i32_16x16x64_i8 v[74:77], v[174:177], v[198:201], v[74:77]
	v_mfma_i32_16x16x64_i8 v[70:73], v[166:169], v[206:209], v[70:73]
	v_mfma_i32_16x16x64_i8 v[66:69], v[174:177], v[206:209], v[66:69]
	v_mfma_i32_16x16x64_i8 v[94:97], v[170:173], v[186:189], v[94:97]
	v_mfma_i32_16x16x64_i8 v[90:93], v[178:181], v[186:189], v[90:93]
	v_mfma_i32_16x16x64_i8 v[86:89], v[170:173], v[194:197], v[86:89]
	v_mfma_i32_16x16x64_i8 v[82:85], v[178:181], v[194:197], v[82:85]
	v_mfma_i32_16x16x64_i8 v[78:81], v[170:173], v[202:205], v[78:81]
	v_mfma_i32_16x16x64_i8 v[74:77], v[178:181], v[202:205], v[74:77]
	v_mfma_i32_16x16x64_i8 v[70:73], v[170:173], v[210:213], v[70:73]
	v_mfma_i32_16x16x64_i8 v[66:69], v[178:181], v[210:213], v[66:69]
	s_setprio 0
	s_barrier
	ds_read_b128 v[182:185], v155 offset:49152
	ds_read_b128 v[186:189], v155 offset:50176
	ds_read_b128 v[190:193], v155 offset:51200
	ds_read_b128 v[194:197], v155 offset:52224
	ds_read_b128 v[198:201], v155 offset:53248
	ds_read_b128 v[202:205], v155 offset:54272
	ds_read_b128 v[206:209], v155 offset:55296
	ds_read_b128 v[210:213], v155 offset:56320
	s_or_b32 s68, s67, 0x80
	s_mov_b32 m0, s41
	s_nop 0
	buffer_load_dwordx4 v145, s[8:11], s68 offen lds
	s_add_i32 s67, s67, 0x20080
	s_mov_b32 m0, s42
	s_nop 0
	buffer_load_dwordx4 v146, s[8:11], s68 offen lds
	s_nop 0
	s_mov_b32 m0, s45
	s_nop 0
	buffer_load_dwordx4 v145, s[8:11], s67 offen lds
	s_nop 0
	s_mov_b32 m0, s46
	s_nop 0
	buffer_load_dwordx4 v146, s[8:11], s67 offen lds
	s_nop 0
	s_mov_b32 m0, s43
	s_nop 0
	buffer_load_dwordx4 v147, s[12:15], s66 offen lds
	s_nop 0
	s_mov_b32 m0, s44
	s_nop 0
	buffer_load_dwordx4 v148, s[12:15], s66 offen lds
	s_waitcnt vmcnt(8)
	s_waitcnt lgkmcnt(0)
	s_barrier
	s_setprio 1
	s_waitcnt lgkmcnt(0)
	v_mfma_i32_16x16x64_i8 v[62:65], v[136:139], v[182:185], v[62:65]
	v_mfma_i32_16x16x64_i8 v[58:61], v[158:161], v[182:185], v[58:61]
	v_mfma_i32_16x16x64_i8 v[54:57], v[136:139], v[190:193], v[54:57]
	v_mfma_i32_16x16x64_i8 v[50:53], v[158:161], v[190:193], v[50:53]
	v_mfma_i32_16x16x64_i8 v[46:49], v[136:139], v[198:201], v[46:49]
	v_mfma_i32_16x16x64_i8 v[42:45], v[158:161], v[198:201], v[42:45]
	v_mfma_i32_16x16x64_i8 v[38:41], v[136:139], v[206:209], v[38:41]
	v_mfma_i32_16x16x64_i8 v[34:37], v[158:161], v[206:209], v[34:37]
	v_mfma_i32_16x16x64_i8 v[62:65], v[140:143], v[186:189], v[62:65]
	v_mfma_i32_16x16x64_i8 v[58:61], v[162:165], v[186:189], v[58:61]
	v_mfma_i32_16x16x64_i8 v[54:57], v[140:143], v[194:197], v[54:57]
	v_mfma_i32_16x16x64_i8 v[50:53], v[162:165], v[194:197], v[50:53]
	v_mfma_i32_16x16x64_i8 v[46:49], v[140:143], v[202:205], v[46:49]
	v_mfma_i32_16x16x64_i8 v[42:45], v[162:165], v[202:205], v[42:45]
	v_mfma_i32_16x16x64_i8 v[38:41], v[140:143], v[210:213], v[38:41]
	v_mfma_i32_16x16x64_i8 v[34:37], v[162:165], v[210:213], v[34:37]
	s_setprio 0
	s_setprio 1
	v_mfma_i32_16x16x64_i8 v[30:33], v[166:169], v[182:185], v[30:33]
	v_mfma_i32_16x16x64_i8 v[26:29], v[174:177], v[182:185], v[26:29]
	v_mfma_i32_16x16x64_i8 v[22:25], v[166:169], v[190:193], v[22:25]
	v_mfma_i32_16x16x64_i8 v[18:21], v[174:177], v[190:193], v[18:21]
	v_mfma_i32_16x16x64_i8 v[14:17], v[166:169], v[198:201], v[14:17]
	v_mfma_i32_16x16x64_i8 v[10:13], v[174:177], v[198:201], v[10:13]
	v_mfma_i32_16x16x64_i8 v[6:9], v[166:169], v[206:209], v[6:9]
	v_mfma_i32_16x16x64_i8 v[2:5], v[174:177], v[206:209], v[2:5]
	v_mfma_i32_16x16x64_i8 v[30:33], v[170:173], v[186:189], v[30:33]
	v_mfma_i32_16x16x64_i8 v[26:29], v[178:181], v[186:189], v[26:29]
	v_mfma_i32_16x16x64_i8 v[22:25], v[170:173], v[194:197], v[22:25]
	v_mfma_i32_16x16x64_i8 v[18:21], v[178:181], v[194:197], v[18:21]
	v_mfma_i32_16x16x64_i8 v[14:17], v[170:173], v[202:205], v[14:17]
	v_mfma_i32_16x16x64_i8 v[10:13], v[178:181], v[202:205], v[10:13]
	v_mfma_i32_16x16x64_i8 v[6:9], v[170:173], v[210:213], v[6:9]
	v_mfma_i32_16x16x64_i8 v[2:5], v[178:181], v[210:213], v[2:5]
	s_setprio 0
	s_barrier
	s_add_i32 s65, s65, 2
	s_addk_i32 s63, 0x100
	s_addk_i32 s64, 0x100
	s_cmp_gt_u32 s65, 5
	s_cbranch_scc0 .LBB0_353
	s_branch .Lafter5

.LBB0_1066:
	v_lshrrev_b32_e32 v4, 1, v2
	v_and_b32_e32 v150, 24, v4
	s_add_u32 s16, s0, 0x5000000
	v_and_b32_e32 v3, 63, v2
	v_and_b32_e32 v148, 15, v2
	v_lshlrev_b32_e32 v4, 1, v150
	v_lshlrev_b32_e32 v2, 2, v2
	s_addc_u32 s17, s1, 0
	s_lshl_b32 s33, s4, 6
	v_lshl_or_b32 v4, v148, 6, v4
	s_lshl_b32 s4, s4, 13
	v_and_b32_e32 v2, 32, v2
	v_bitop3_b32 v5, v4, s4, v2 bitop3:0xde
	s_lshl_b32 s4, s21, 5
	s_and_b32 s34, s4, 0x60
	s_lshl_b32 s4, s34, 7
	v_bitop3_b32 v4, v4, s4, v2 bitop3:0xde
	s_waitcnt vmcnt(2)
	s_barrier
	s_add_i32 s35, s26, 0x18000
	s_or_b32 s4, s58, 0x80
	s_mov_b32 m0, s35
	s_nop 0
	buffer_load_dwordx4 v144, s[8:11], s4 offen lds
	s_add_i32 s36, s26, 0x1a000
	s_mov_b32 m0, s36
	s_nop 0
	buffer_load_dwordx4 v145, s[8:11], s4 offen lds
	s_add_i32 s37, s26, 0x8000
	s_or_b32 s4, s55, 0x80
	s_mov_b32 m0, s37
	s_nop 0
	buffer_load_dwordx4 v146, s[12:15], s4 offen lds
	s_add_i32 s38, s26, 0xa000
	s_mov_b32 m0, s38
	s_nop 0
	buffer_load_dwordx4 v147, s[12:15], s4 offen lds
	s_add_i32 s39, s26, 0x1c000
	s_or_b32 s4, s58, 0x20080
	s_add_i32 s40, s26, 0x1e000
	s_cmp_lt_i32 s21, 4
	s_cselect_b64 s[18:19], -1, 0
	s_and_b32 s22, s20, 0xffffffc0
	s_lshl_b32 s41, s21, 8
	s_add_i32 s42, s26, 0xc000
	s_add_i32 s45, s22, 0xffffff00
	s_ashr_i32 s46, s22, 31
	s_cmpk_lt_u32 s20, 0x100
	s_mov_b32 m0, s39
	s_nop 0
	buffer_load_dwordx4 v144, s[8:11], s4 offen lds
	s_cselect_b64 s[20:21], -1, 0
	s_add_i32 s43, s26, 0xe000
	s_ashr_i32 s44, s23, 31
	s_mov_b32 m0, s40
	s_nop 0
	buffer_load_dwordx4 v145, s[8:11], s4 offen lds
	s_mov_b32 s47, 0xfc00000
	s_and_b64 s[4:5], s[18:19], exec
	s_cselect_b32 s4, s47, 0xfc25800
	s_add_u32 s4, s0, s4
	s_addc_u32 s5, s1, 0
	s_and_b64 s[0:1], s[18:19], exec
	s_cselect_b32 s1, s46, 0
	s_cselect_b32 s0, s22, s45
	s_lshl_b64 s[0:1], s[0:1], 2
	s_add_u32 s0, s4, s0
	s_waitcnt vmcnt(6)
	s_addc_u32 s1, s5, s1
	v_lshlrev_b32_e32 v2, 2, v3
	v_mov_b32_e32 v3, 0
	v_lshl_add_u64 v[130:131], s[0:1], 0, v[2:3]
	v_add_u32_e32 v2, 0, v4
	v_or_b32_e32 v149, s33, v148
	v_or_b32_e32 v151, s34, v150
	v_mov_b64_e32 v[132:133], 0x580
	v_mov_b64_e32 v[134:135], 0x57f
	s_movk_i32 s45, 0xb1
	v_add_u32_e32 v152, 0x10000, v2
	v_add_u32_e32 v153, 0x14000, v2
	v_add_u32_e32 v154, 0, v5
	v_add_u32_e32 v155, 0x18000, v2
	v_add_u32_e32 v156, 0x1c000, v2
	s_movk_i32 s46, 0x1600
	s_mov_b32 s22, 0xbfb8aa3b
	s_barrier
	s_mov_b32 s32, 0
	s_branch .LBB0_1069

.LBB0_1068:
	s_mov_b32 s32, 1
	s_andn2_b64 vcc, exec, s[0:1]
	s_mov_b32 s52, s48
	s_mov_b32 s53, s49
	s_mov_b32 s58, s51
	s_mov_b32 s55, s50
	s_mov_b32 s50, s47
	s_cbranch_vccz .LBB0_1078

.LBB0_1071:
	s_and_b64 s[0:1], s[18:19], exec
	s_cselect_b32 s0, s53, s52
	s_lshl_b32 s0, s0, 8
	s_ashr_i32 s1, s0, 31
	v_lshl_add_u64 v[2:3], s[0:1], 2, v[130:131]
	s_lshl_b32 s0, s50, 11
	s_and_b32 s0, s0, 0x800
	s_add_i32 s0, s0, 0
	s_add_i32 s0, s0, 0x20000
	s_add_i32 m0, s0, s41
	s_lshl_b32 s50, s49, 19
	global_load_lds_dword v[2:3], off
	s_or_b32 s1, s55, 0x300
	s_and_b64 s[60:61], s[4:5], exec
	s_cselect_b32 s1, s50, s1
	s_lshl_b32 s51, s48, 18
	s_or_b32 s54, s58, 0x300
	s_and_b64 s[60:61], s[4:5], exec
	v_mov_b32_e32 v2, 0
	s_cselect_b32 s54, s51, s54
	s_add_i32 s55, s55, 0x20080
	s_addk_i32 s58, 0x100
	s_mov_b32 s59, -2
	v_mov_b32_e32 v3, v2
	v_mov_b32_e32 v4, v2
	v_mov_b32_e32 v5, v2
	v_mov_b32_e32 v6, v2
	v_mov_b32_e32 v7, v2
	v_mov_b32_e32 v8, v2
	v_mov_b32_e32 v9, v2
	v_mov_b32_e32 v10, v2
	v_mov_b32_e32 v11, v2
	v_mov_b32_e32 v12, v2
	v_mov_b32_e32 v13, v2
	v_mov_b32_e32 v14, v2
	v_mov_b32_e32 v15, v2
	v_mov_b32_e32 v16, v2
	v_mov_b32_e32 v17, v2
	v_mov_b32_e32 v18, v2
	v_mov_b32_e32 v19, v2
	v_mov_b32_e32 v20, v2
	v_mov_b32_e32 v21, v2
	v_mov_b32_e32 v22, v2
	v_mov_b32_e32 v23, v2
	v_mov_b32_e32 v24, v2
	v_mov_b32_e32 v25, v2
	v_mov_b32_e32 v26, v2
	v_mov_b32_e32 v27, v2
	v_mov_b32_e32 v28, v2
	v_mov_b32_e32 v29, v2
	v_mov_b32_e32 v30, v2
	v_mov_b32_e32 v31, v2
	v_mov_b32_e32 v32, v2
	v_mov_b32_e32 v33, v2
	v_mov_b32_e32 v34, v2
	v_mov_b32_e32 v35, v2
	v_mov_b32_e32 v36, v2
	v_mov_b32_e32 v37, v2
	v_mov_b32_e32 v38, v2
	v_mov_b32_e32 v39, v2
	v_mov_b32_e32 v40, v2
	v_mov_b32_e32 v41, v2
	v_mov_b32_e32 v42, v2
	v_mov_b32_e32 v43, v2
	v_mov_b32_e32 v44, v2
	v_mov_b32_e32 v45, v2
	v_mov_b32_e32 v46, v2
	v_mov_b32_e32 v47, v2
	v_mov_b32_e32 v48, v2
	v_mov_b32_e32 v49, v2
	v_mov_b32_e32 v50, v2
	v_mov_b32_e32 v51, v2
	v_mov_b32_e32 v52, v2
	v_mov_b32_e32 v53, v2
	v_mov_b32_e32 v54, v2
	v_mov_b32_e32 v55, v2
	v_mov_b32_e32 v56, v2
	v_mov_b32_e32 v57, v2
	v_mov_b32_e32 v58, v2
	v_mov_b32_e32 v59, v2
	v_mov_b32_e32 v60, v2
	v_mov_b32_e32 v61, v2
	v_mov_b32_e32 v62, v2
	v_mov_b32_e32 v63, v2
	v_mov_b32_e32 v64, v2
	v_mov_b32_e32 v65, v2
	v_mov_b32_e32 v66, v2
	v_mov_b32_e32 v67, v2
	v_mov_b32_e32 v68, v2
	v_mov_b32_e32 v69, v2
	v_mov_b32_e32 v70, v2
	v_mov_b32_e32 v71, v2
	v_mov_b32_e32 v72, v2
	v_mov_b32_e32 v73, v2
	v_mov_b32_e32 v74, v2
	v_mov_b32_e32 v75, v2
	v_mov_b32_e32 v76, v2
	v_mov_b32_e32 v77, v2
	v_mov_b32_e32 v78, v2
	v_mov_b32_e32 v79, v2
	v_mov_b32_e32 v80, v2
	v_mov_b32_e32 v81, v2
	v_mov_b32_e32 v82, v2
	v_mov_b32_e32 v83, v2
	v_mov_b32_e32 v84, v2
	v_mov_b32_e32 v85, v2
	v_mov_b32_e32 v86, v2
	v_mov_b32_e32 v87, v2
	v_mov_b32_e32 v88, v2
	v_mov_b32_e32 v89, v2
	v_mov_b32_e32 v90, v2
	v_mov_b32_e32 v91, v2
	v_mov_b32_e32 v92, v2
	v_mov_b32_e32 v93, v2
	v_mov_b32_e32 v94, v2
	v_mov_b32_e32 v95, v2
	v_mov_b32_e32 v96, v2
	v_mov_b32_e32 v97, v2
	v_mov_b32_e32 v98, v2
	v_mov_b32_e32 v99, v2
	v_mov_b32_e32 v100, v2
	v_mov_b32_e32 v101, v2
	v_mov_b32_e32 v102, v2
	v_mov_b32_e32 v103, v2
	v_mov_b32_e32 v104, v2
	v_mov_b32_e32 v105, v2
	v_mov_b32_e32 v106, v2
	v_mov_b32_e32 v107, v2
	v_mov_b32_e32 v108, v2
	v_mov_b32_e32 v109, v2
	v_mov_b32_e32 v110, v2
	v_mov_b32_e32 v111, v2
	v_mov_b32_e32 v112, v2
	v_mov_b32_e32 v113, v2
	v_mov_b32_e32 v114, v2
	v_mov_b32_e32 v115, v2
	v_mov_b32_e32 v116, v2
	v_mov_b32_e32 v117, v2
	v_mov_b32_e32 v118, v2
	v_mov_b32_e32 v119, v2
	v_mov_b32_e32 v120, v2
	v_mov_b32_e32 v121, v2
	v_mov_b32_e32 v122, v2
	v_mov_b32_e32 v123, v2
	v_mov_b32_e32 v124, v2
	v_mov_b32_e32 v125, v2
	v_mov_b32_e32 v126, v2
	v_mov_b32_e32 v127, v2
	v_mov_b32_e32 v128, v2
	v_mov_b32_e32 v129, v2
	s_cmp_eq_u32 s32, 1
	s_cbranch_scc1 .Lpeel12

.Lafter12:
	s_and_b64 vcc, exec, s[20:21]
	s_cbranch_vccz .LBB0_1075
	s_barrier

.Lpeel12:
	ds_read_b128 v[136:139], v152
	ds_read_b128 v[140:143], v152 offset:1024
	ds_read_b128 v[158:161], v152 offset:2048
	ds_read_b128 v[162:165], v152 offset:3072
	ds_read_b128 v[166:169], v153
	ds_read_b128 v[170:173], v153 offset:1024
	ds_read_b128 v[174:177], v153 offset:2048
	ds_read_b128 v[178:181], v153 offset:3072
	s_add_i32 s60, s55, 0xfffe0080
	s_cmp_eq_u32 s59, 4
	s_cselect_b32 s62, s1, s60
	s_cselect_b32 s61, s54, s58
	s_or_b32 s60, s62, 0x80
	ds_read_b128 v[182:185], v154
	ds_read_b128 v[186:189], v154 offset:1024
	ds_read_b128 v[190:193], v154 offset:2048
	ds_read_b128 v[194:197], v154 offset:3072
	ds_read_b128 v[198:201], v154 offset:4096
	ds_read_b128 v[202:205], v154 offset:5120
	ds_read_b128 v[206:209], v154 offset:6144
	ds_read_b128 v[210:213], v154 offset:7168
	s_mov_b32 m0, s42
	s_nop 0
	buffer_load_dwordx4 v146, s[12:15], s55 offen lds
	s_nop 0
	s_mov_b32 m0, s43
	s_nop 0
	buffer_load_dwordx4 v147, s[12:15], s55 offen lds
	s_waitcnt vmcnt(17)
	s_waitcnt lgkmcnt(0)
	s_barrier
	s_setprio 1
	s_waitcnt lgkmcnt(0)
	v_mfma_i32_16x16x64_i8 v[126:129], v[136:139], v[182:185], v[126:129]
	v_mfma_i32_16x16x64_i8 v[122:125], v[158:161], v[182:185], v[122:125]
	v_mfma_i32_16x16x64_i8 v[118:121], v[136:139], v[190:193], v[118:121]
	v_mfma_i32_16x16x64_i8 v[114:117], v[158:161], v[190:193], v[114:117]
	v_mfma_i32_16x16x64_i8 v[110:113], v[136:139], v[198:201], v[110:113]
	v_mfma_i32_16x16x64_i8 v[106:109], v[158:161], v[198:201], v[106:109]
	v_mfma_i32_16x16x64_i8 v[102:105], v[136:139], v[206:209], v[102:105]
	v_mfma_i32_16x16x64_i8 v[98:101], v[158:161], v[206:209], v[98:101]
	v_mfma_i32_16x16x64_i8 v[126:129], v[140:143], v[186:189], v[126:129]
	v_mfma_i32_16x16x64_i8 v[122:125], v[162:165], v[186:189], v[122:125]
	v_mfma_i32_16x16x64_i8 v[118:121], v[140:143], v[194:197], v[118:121]
	v_mfma_i32_16x16x64_i8 v[114:117], v[162:165], v[194:197], v[114:117]
	v_mfma_i32_16x16x64_i8 v[110:113], v[140:143], v[202:205], v[110:113]
	v_mfma_i32_16x16x64_i8 v[106:109], v[162:165], v[202:205], v[106:109]
	v_mfma_i32_16x16x64_i8 v[102:105], v[140:143], v[210:213], v[102:105]
	v_mfma_i32_16x16x64_i8 v[98:101], v[162:165], v[210:213], v[98:101]
	s_setprio 0
	s_setprio 1
	v_mfma_i32_16x16x64_i8 v[94:97], v[166:169], v[182:185], v[94:97]
	v_mfma_i32_16x16x64_i8 v[90:93], v[174:177], v[182:185], v[90:93]
	v_mfma_i32_16x16x64_i8 v[86:89], v[166:169], v[190:193], v[86:89]
	v_mfma_i32_16x16x64_i8 v[82:85], v[174:177], v[190:193], v[82:85]
	v_mfma_i32_16x16x64_i8 v[78:81], v[166:169], v[198:201], v[78:81]
	v_mfma_i32_16x16x64_i8 v[74:77], v[174:177], v[198:201], v[74:77]
	v_mfma_i32_16x16x64_i8 v[70:73], v[166:169], v[206:209], v[70:73]
	v_mfma_i32_16x16x64_i8 v[66:69], v[174:177], v[206:209], v[66:69]
	v_mfma_i32_16x16x64_i8 v[94:97], v[170:173], v[186:189], v[94:97]
	v_mfma_i32_16x16x64_i8 v[90:93], v[178:181], v[186:189], v[90:93]
	v_mfma_i32_16x16x64_i8 v[86:89], v[170:173], v[194:197], v[86:89]
	v_mfma_i32_16x16x64_i8 v[82:85], v[178:181], v[194:197], v[82:85]
	v_mfma_i32_16x16x64_i8 v[78:81], v[170:173], v[202:205], v[78:81]
	v_mfma_i32_16x16x64_i8 v[74:77], v[178:181], v[202:205], v[74:77]
	v_mfma_i32_16x16x64_i8 v[70:73], v[170:173], v[210:213], v[70:73]
	v_mfma_i32_16x16x64_i8 v[66:69], v[178:181], v[210:213], v[66:69]
	s_setprio 0
	s_barrier
	ds_read_b128 v[182:185], v154 offset:16384
	ds_read_b128 v[186:189], v154 offset:17408
	ds_read_b128 v[190:193], v154 offset:18432
	ds_read_b128 v[194:197], v154 offset:19456
	ds_read_b128 v[198:201], v154 offset:20480
	ds_read_b128 v[202:205], v154 offset:21504
	ds_read_b128 v[206:209], v154 offset:22528
	ds_read_b128 v[210:213], v154 offset:23552
	s_mov_b32 m0, s27
	s_nop 0
	buffer_load_dwordx4 v144, s[8:11], s61 offen lds
	s_add_i32 s63, s61, 0x20000
	s_mov_b32 m0, s28
	s_nop 0
	buffer_load_dwordx4 v145, s[8:11], s61 offen lds
	s_nop 0
	s_mov_b32 m0, s29
	s_nop 0
	buffer_load_dwordx4 v144, s[8:11], s63 offen lds
	s_nop 0
	s_mov_b32 m0, s30
	s_nop 0
	buffer_load_dwordx4 v145, s[8:11], s63 offen lds
	s_nop 0
	s_mov_b32 m0, s26
	s_nop 0
	buffer_load_dwordx4 v146, s[12:15], s62 offen lds
	s_nop 0
	s_mov_b32 m0, s2
	s_nop 0
	buffer_load_dwordx4 v147, s[12:15], s62 offen lds
	s_waitcnt vmcnt(17)
	s_waitcnt lgkmcnt(0)
	s_barrier
	s_setprio 1
	s_waitcnt lgkmcnt(0)
	v_mfma_i32_16x16x64_i8 v[62:65], v[136:139], v[182:185], v[62:65]
	v_mfma_i32_16x16x64_i8 v[58:61], v[158:161], v[182:185], v[58:61]
	v_mfma_i32_16x16x64_i8 v[54:57], v[136:139], v[190:193], v[54:57]
	v_mfma_i32_16x16x64_i8 v[50:53], v[158:161], v[190:193], v[50:53]
	v_mfma_i32_16x16x64_i8 v[46:49], v[136:139], v[198:201], v[46:49]
	v_mfma_i32_16x16x64_i8 v[42:45], v[158:161], v[198:201], v[42:45]
	v_mfma_i32_16x16x64_i8 v[38:41], v[136:139], v[206:209], v[38:41]
	v_mfma_i32_16x16x64_i8 v[34:37], v[158:161], v[206:209], v[34:37]
	v_mfma_i32_16x16x64_i8 v[62:65], v[140:143], v[186:189], v[62:65]
	v_mfma_i32_16x16x64_i8 v[58:61], v[162:165], v[186:189], v[58:61]
	v_mfma_i32_16x16x64_i8 v[54:57], v[140:143], v[194:197], v[54:57]
	v_mfma_i32_16x16x64_i8 v[50:53], v[162:165], v[194:197], v[50:53]
	v_mfma_i32_16x16x64_i8 v[46:49], v[140:143], v[202:205], v[46:49]
	v_mfma_i32_16x16x64_i8 v[42:45], v[162:165], v[202:205], v[42:45]
	v_mfma_i32_16x16x64_i8 v[38:41], v[140:143], v[210:213], v[38:41]
	v_mfma_i32_16x16x64_i8 v[34:37], v[162:165], v[210:213], v[34:37]
	s_setprio 0
	s_setprio 1
	v_mfma_i32_16x16x64_i8 v[30:33], v[166:169], v[182:185], v[30:33]
	v_mfma_i32_16x16x64_i8 v[26:29], v[174:177], v[182:185], v[26:29]
	v_mfma_i32_16x16x64_i8 v[22:25], v[166:169], v[190:193], v[22:25]
	v_mfma_i32_16x16x64_i8 v[18:21], v[174:177], v[190:193], v[18:21]
	v_mfma_i32_16x16x64_i8 v[14:17], v[166:169], v[198:201], v[14:17]
	v_mfma_i32_16x16x64_i8 v[10:13], v[174:177], v[198:201], v[10:13]
	v_mfma_i32_16x16x64_i8 v[6:9], v[166:169], v[206:209], v[6:9]
	v_mfma_i32_16x16x64_i8 v[2:5], v[174:177], v[206:209], v[2:5]
	v_mfma_i32_16x16x64_i8 v[30:33], v[170:173], v[186:189], v[30:33]
	v_mfma_i32_16x16x64_i8 v[26:29], v[178:181], v[186:189], v[26:29]
	v_mfma_i32_16x16x64_i8 v[22:25], v[170:173], v[194:197], v[22:25]
	v_mfma_i32_16x16x64_i8 v[18:21], v[178:181], v[194:197], v[18:21]
	v_mfma_i32_16x16x64_i8 v[14:17], v[170:173], v[202:205], v[14:17]
	v_mfma_i32_16x16x64_i8 v[10:13], v[178:181], v[202:205], v[10:13]
	v_mfma_i32_16x16x64_i8 v[6:9], v[170:173], v[210:213], v[6:9]
	v_mfma_i32_16x16x64_i8 v[2:5], v[178:181], v[210:213], v[2:5]
	s_setprio 0
	s_barrier
	ds_read_b128 v[136:139], v155
	ds_read_b128 v[140:143], v155 offset:1024
	ds_read_b128 v[158:161], v155 offset:2048
	ds_read_b128 v[162:165], v155 offset:3072
	ds_read_b128 v[166:169], v156
	ds_read_b128 v[170:173], v156 offset:1024
	ds_read_b128 v[174:177], v156 offset:2048
	ds_read_b128 v[178:181], v156 offset:3072
	ds_read_b128 v[182:185], v154 offset:32768
	ds_read_b128 v[186:189], v154 offset:33792
	ds_read_b128 v[190:193], v154 offset:34816
	ds_read_b128 v[194:197], v154 offset:35840
	ds_read_b128 v[198:201], v154 offset:36864
	ds_read_b128 v[202:205], v154 offset:37888
	ds_read_b128 v[206:209], v154 offset:38912
	ds_read_b128 v[210:213], v154 offset:39936
	s_add_i32 s62, s62, 0x20000
	s_mov_b32 m0, s3
	s_nop 0
	buffer_load_dwordx4 v146, s[12:15], s62 offen lds
	s_nop 0
	s_mov_b32 m0, s31
	s_nop 0
	buffer_load_dwordx4 v147, s[12:15], s62 offen lds
	s_waitcnt vmcnt(8)
	s_waitcnt lgkmcnt(0)
	s_barrier
	s_setprio 1
	s_waitcnt lgkmcnt(0)
	v_mfma_i32_16x16x64_i8 v[126:129], v[136:139], v[182:185], v[126:129]
	v_mfma_i32_16x16x64_i8 v[122:125], v[158:161], v[182:185], v[122:125]
	v_mfma_i32_16x16x64_i8 v[118:121], v[136:139], v[190:193], v[118:121]
	v_mfma_i32_16x16x64_i8 v[114:117], v[158:161], v[190:193], v[114:117]
	v_mfma_i32_16x16x64_i8 v[110:113], v[136:139], v[198:201], v[110:113]
	v_mfma_i32_16x16x64_i8 v[106:109], v[158:161], v[198:201], v[106:109]
	v_mfma_i32_16x16x64_i8 v[102:105], v[136:139], v[206:209], v[102:105]
	v_mfma_i32_16x16x64_i8 v[98:101], v[158:161], v[206:209], v[98:101]
	v_mfma_i32_16x16x64_i8 v[126:129], v[140:143], v[186:189], v[126:129]
	v_mfma_i32_16x16x64_i8 v[122:125], v[162:165], v[186:189], v[122:125]
	v_mfma_i32_16x16x64_i8 v[118:121], v[140:143], v[194:197], v[118:121]
	v_mfma_i32_16x16x64_i8 v[114:117], v[162:165], v[194:197], v[114:117]
	v_mfma_i32_16x16x64_i8 v[110:113], v[140:143], v[202:205], v[110:113]
	v_mfma_i32_16x16x64_i8 v[106:109], v[162:165], v[202:205], v[106:109]
	v_mfma_i32_16x16x64_i8 v[102:105], v[140:143], v[210:213], v[102:105]
	v_mfma_i32_16x16x64_i8 v[98:101], v[162:165], v[210:213], v[98:101]
	s_setprio 0
	s_setprio 1
	v_mfma_i32_16x16x64_i8 v[94:97], v[166:169], v[182:185], v[94:97]
	v_mfma_i32_16x16x64_i8 v[90:93], v[174:177], v[182:185], v[90:93]
	v_mfma_i32_16x16x64_i8 v[86:89], v[166:169], v[190:193], v[86:89]
	v_mfma_i32_16x16x64_i8 v[82:85], v[174:177], v[190:193], v[82:85]
	v_mfma_i32_16x16x64_i8 v[78:81], v[166:169], v[198:201], v[78:81]
	v_mfma_i32_16x16x64_i8 v[74:77], v[174:177], v[198:201], v[74:77]
	v_mfma_i32_16x16x64_i8 v[70:73], v[166:169], v[206:209], v[70:73]
	v_mfma_i32_16x16x64_i8 v[66:69], v[174:177], v[206:209], v[66:69]
	v_mfma_i32_16x16x64_i8 v[94:97], v[170:173], v[186:189], v[94:97]
	v_mfma_i32_16x16x64_i8 v[90:93], v[178:181], v[186:189], v[90:93]
	v_mfma_i32_16x16x64_i8 v[86:89], v[170:173], v[194:197], v[86:89]
	v_mfma_i32_16x16x64_i8 v[82:85], v[178:181], v[194:197], v[82:85]
	v_mfma_i32_16x16x64_i8 v[78:81], v[170:173], v[202:205], v[78:81]
	v_mfma_i32_16x16x64_i8 v[74:77], v[178:181], v[202:205], v[74:77]
	v_mfma_i32_16x16x64_i8 v[70:73], v[170:173], v[210:213], v[70:73]
	v_mfma_i32_16x16x64_i8 v[66:69], v[178:181], v[210:213], v[66:69]
	s_setprio 0
	s_barrier
	ds_read_b128 v[182:185], v154 offset:49152
	ds_read_b128 v[186:189], v154 offset:50176
	ds_read_b128 v[190:193], v154 offset:51200
	ds_read_b128 v[194:197], v154 offset:52224
	ds_read_b128 v[198:201], v154 offset:53248
	ds_read_b128 v[202:205], v154 offset:54272
	ds_read_b128 v[206:209], v154 offset:55296
	ds_read_b128 v[210:213], v154 offset:56320
	s_or_b32 s62, s61, 0x80
	s_mov_b32 m0, s35
	s_nop 0
	buffer_load_dwordx4 v144, s[8:11], s62 offen lds
	s_add_i32 s61, s61, 0x20080
	s_mov_b32 m0, s36
	s_nop 0
	buffer_load_dwordx4 v145, s[8:11], s62 offen lds
	s_nop 0
	s_mov_b32 m0, s39
	s_nop 0
	buffer_load_dwordx4 v144, s[8:11], s61 offen lds
	s_nop 0
	s_mov_b32 m0, s40
	s_nop 0
	buffer_load_dwordx4 v145, s[8:11], s61 offen lds
	s_nop 0
	s_mov_b32 m0, s37
	s_nop 0
	buffer_load_dwordx4 v146, s[12:15], s60 offen lds
	s_nop 0
	s_mov_b32 m0, s38
	s_nop 0
	buffer_load_dwordx4 v147, s[12:15], s60 offen lds
	s_waitcnt vmcnt(8)
	s_waitcnt lgkmcnt(0)
	s_barrier
	s_setprio 1
	s_waitcnt lgkmcnt(0)
	v_mfma_i32_16x16x64_i8 v[62:65], v[136:139], v[182:185], v[62:65]
	v_mfma_i32_16x16x64_i8 v[58:61], v[158:161], v[182:185], v[58:61]
	v_mfma_i32_16x16x64_i8 v[54:57], v[136:139], v[190:193], v[54:57]
	v_mfma_i32_16x16x64_i8 v[50:53], v[158:161], v[190:193], v[50:53]
	v_mfma_i32_16x16x64_i8 v[46:49], v[136:139], v[198:201], v[46:49]
	v_mfma_i32_16x16x64_i8 v[42:45], v[158:161], v[198:201], v[42:45]
	v_mfma_i32_16x16x64_i8 v[38:41], v[136:139], v[206:209], v[38:41]
	v_mfma_i32_16x16x64_i8 v[34:37], v[158:161], v[206:209], v[34:37]
	v_mfma_i32_16x16x64_i8 v[62:65], v[140:143], v[186:189], v[62:65]
	v_mfma_i32_16x16x64_i8 v[58:61], v[162:165], v[186:189], v[58:61]
	v_mfma_i32_16x16x64_i8 v[54:57], v[140:143], v[194:197], v[54:57]
	v_mfma_i32_16x16x64_i8 v[50:53], v[162:165], v[194:197], v[50:53]
	v_mfma_i32_16x16x64_i8 v[46:49], v[140:143], v[202:205], v[46:49]
	v_mfma_i32_16x16x64_i8 v[42:45], v[162:165], v[202:205], v[42:45]
	v_mfma_i32_16x16x64_i8 v[38:41], v[140:143], v[210:213], v[38:41]
	v_mfma_i32_16x16x64_i8 v[34:37], v[162:165], v[210:213], v[34:37]
	s_setprio 0
	s_setprio 1
	v_mfma_i32_16x16x64_i8 v[30:33], v[166:169], v[182:185], v[30:33]
	v_mfma_i32_16x16x64_i8 v[26:29], v[174:177], v[182:185], v[26:29]
	v_mfma_i32_16x16x64_i8 v[22:25], v[166:169], v[190:193], v[22:25]
	v_mfma_i32_16x16x64_i8 v[18:21], v[174:177], v[190:193], v[18:21]
	v_mfma_i32_16x16x64_i8 v[14:17], v[166:169], v[198:201], v[14:17]
	v_mfma_i32_16x16x64_i8 v[10:13], v[174:177], v[198:201], v[10:13]
	v_mfma_i32_16x16x64_i8 v[6:9], v[166:169], v[206:209], v[6:9]
	v_mfma_i32_16x16x64_i8 v[2:5], v[174:177], v[206:209], v[2:5]
	v_mfma_i32_16x16x64_i8 v[30:33], v[170:173], v[186:189], v[30:33]
	v_mfma_i32_16x16x64_i8 v[26:29], v[178:181], v[186:189], v[26:29]
	v_mfma_i32_16x16x64_i8 v[22:25], v[170:173], v[194:197], v[22:25]
	v_mfma_i32_16x16x64_i8 v[18:21], v[178:181], v[194:197], v[18:21]
	v_mfma_i32_16x16x64_i8 v[14:17], v[170:173], v[202:205], v[14:17]
	v_mfma_i32_16x16x64_i8 v[10:13], v[178:181], v[202:205], v[10:13]
	v_mfma_i32_16x16x64_i8 v[6:9], v[170:173], v[210:213], v[6:9]
	v_mfma_i32_16x16x64_i8 v[2:5], v[178:181], v[210:213], v[2:5]
	s_setprio 0
	s_barrier
	s_add_i32 s59, s59, 2
	s_addk_i32 s55, 0x100
	s_addk_i32 s58, 0x100
	s_cmp_gt_u32 s59, 5
	s_cbranch_scc0 .LBB0_1072
	s_branch .Lafter12
